# mlstm_out q/k conv arms merged into one pass (per-lane base/scale/LDS dst) + stage-3 unit counter fetched one unit ahead
# speedup vs baseline: 1.0140x; 1.0140x over previous
; __device__ __forceinline__ void phase_f(const Params& p, int layer, char* smem, unsigned xcc) {
;     ...
;     bool ml_ready = false;
;     while (true) {
;         if (threadIdx.x == 0) s_unit = (int)atomicAdd(ctrC, 1u);
;         __syncthreads();
;         const int u = s_unit;
;         __syncthreads();
;         if (u >= 4352) break;
.LBB0_468:
	s_mov_b64 s[34:35], 0
	v_readlane_b32 s100, v250, 0
	v_readlane_b32 s101, v250, 1
	s_mov_b64 s[98:99], exec
	s_nop 1
	s_and_b64 exec, exec, s[100:101]
	s_cbranch_execz .Lpf3_skipa
	v_readlane_b32 s100, v254, 36
	v_readlane_b32 s101, v254, 37
	v_mov_b32_e32 v235, 1
	s_nop 4
	global_atomic_add v234, v105, v235, s[100:101] offset:4 sc0
.Lpf3_skipa:
	s_mov_b64 exec, s[98:99]
	s_branch .LBB0_472

; __device__ __forceinline__ void phase_f(const Params& p, int layer, char* smem, unsigned xcc) {
;     ...
;     while (true) {
;         if (threadIdx.x == 0) s_unit = (int)atomicAdd(ctrC, 1u);
;         __syncthreads();
;         const int u = s_unit;
;         __syncthreads();
;         if (u >= 4352) break;
.LBB0_472:
	s_mov_b64 s[0:1], exec
	v_readlane_b32 s30, v250, 0
	v_readlane_b32 s31, v250, 1
	s_and_b64 s[30:31], s[0:1], s[30:31]
	s_mov_b64 exec, s[30:31]
	s_cbranch_execz .LBB0_476
	s_mov_b64 s[42:43], exec
	v_mbcnt_lo_u32_b32 v0, s42, 0
	v_mbcnt_hi_u32_b32 v0, s43, v0
	v_cmp_eq_u32_e32 vcc, 0, v0
	s_and_saveexec_b64 s[30:31], vcc
	s_cbranch_execz .LBB0_475
	s_bcnt1_i32_b64 s42, s[42:43]
	v_readlane_b32 s4, v254, 36
	v_mov_b32_e32 v1, s42
	v_readlane_b32 s5, v254, 37
	s_nop 4
	s_waitcnt vmcnt(0)
	v_mov_b32_e32 v1, v234

; __device__ __forceinline__ void mlstm_out_unit(const Params& p, int layer, int uci, char* smem) {
;     ...
;     const int ci = uci % 68, bhd = uci / 68, b = bhd >> 3, h = (bhd >> 1) & 3, d = bhd & 1;
;     float* F = (float*)(smem + MO_F);
;     __syncthreads();
;     float* slot = (float*)(p.ws + OFF_HM) + (size_t)uci * 2048;
;     const float* mls = (const float*)(p.ws + OFF_MLS2) + (size_t)uci * 36;
;     const float mst = mls[33];
;     {
;         const bf16_t* zm = (const bf16_t*)(p.ws + OFF_ZM);
;         const float* cw = p.in[29] + (size_t)layer * 3 * 256; const float* cb = p.in[30] + (size_t)layer * 256;
;         const int s = tid >> 2, part = tid & 3;
;         const int t = step_tok(ci * 64 + s, d);
;         const int lo = t < CTX ? 0 : CTX, hi = t < CTX ? CTX : TT;
;         const bool hp = t > lo, hn = t + 1 < hi;
;         const bf16_t* zr = zm + ((size_t)b * TT + t) * 784;
;         if (part < 2) { const int kc = part * 16;
;             *(uint4*)(smem + MO_Q + s * 80 + kc * 2) = conv8_bf(zr, h * 32 + kc, hp, hn, cw, cb, 0.17677669529663687f);
;             *(uint4*)(smem + MO_Q + s * 80 + kc * 2 + 16) = conv8_bf(zr, h * 32 + kc + 8, hp, hn, cw, cb, 0.17677669529663687f); }
;         else { const int kc = (part - 2) * 16;
;             *(uint4*)(smem + MO_K + s * 80 + kc * 2) = conv8_bf(zr, 128 + h * 32 + kc, hp, hn, cw, cb, 1.f);
;             *(uint4*)(smem + MO_K + s * 80 + kc * 2 + 16) = conv8_bf(zr, 128 + h * 32 + kc + 8, hp, hn, cw, cb, 1.f); }
; __device__ __forceinline__ void phase_f(const Params& p, int layer, char* smem, unsigned xcc) {
;     ...
;         if (threadIdx.x == 0) s_unit = (int)atomicAdd(ctrC, 1u);
;         __syncthreads();
;         const int u = s_unit;
;         __syncthreads();
;         if (u >= 4352) break;
;         if (!ml_ready) {
;             if (threadIdx.x < 64) { unsigned* fl = cw + 64 + layer * 64 + threadIdx.x; while (__hip_atomic_load(fl, __ATOMIC_RELAXED, __HIP_MEMORY_SCOPE_AGENT) == 0u) __builtin_amdgcn_s_sleep(8); }
;             __syncthreads();
;             __threadfence();
;             ml_ready = true;
;         }
;         if (!(layer == 1 && (u % 68) < 4)) mlstm_out_unit(p, layer, u, smem);
.LBB0_483:
	v_readlane_b32 s100, v250, 0
	v_readlane_b32 s101, v250, 1
	s_mov_b64 s[98:99], exec
	s_nop 1
	s_and_b64 exec, exec, s[100:101]
	s_cbranch_execz .Lpf3_skipb
	v_readlane_b32 s100, v254, 36
	v_readlane_b32 s101, v254, 37
	v_mov_b32_e32 v235, 1
	s_nop 4
	global_atomic_add v234, v105, v235, s[100:101] offset:4 sc0
.Lpf3_skipb:
	s_mov_b64 exec, s[98:99]
	s_mul_hi_i32 s1, s0, 0x78787879
	s_lshr_b32 s30, s1, 31
	s_ashr_i32 s1, s1, 5
	s_add_i32 s30, s1, s30
	s_mul_i32 s1, s30, 0x44
	s_sub_i32 s1, s0, s1
	s_cmp_lt_i32 s1, 4
	s_cselect_b64 s[34:35], -1, 0
	s_and_b64 s[34:35], s[12:13], s[34:35]
	s_and_b64 vcc, exec, s[34:35]
	s_cbranch_vccnz .LBB0_470
	s_ashr_i32 s31, s30, 3
	s_bfe_u32 s50, s30, 0x20001
	s_and_b32 s51, s30, 1
	s_mul_i32 s34, s0, 0x90
	v_readlane_b32 s4, v251, 52
	s_mul_hi_i32 s30, s0, 0x90
	s_add_u32 s48, s4, s34
	v_readlane_b32 s4, v251, 53
	s_waitcnt vmcnt(11)
	v_mov_b32_e32 v28, v109
	s_addc_u32 s49, s4, s30
	s_barrier
	global_load_dword v40, v105, s[48:49] offset:132
	v_ashrrev_i32_e32 v31, 2, v28
	v_lshl_add_u32 v0, s1, 6, v31
	v_cmp_lt_i32_e32 vcc, s2, v0
	s_cmp_eq_u32 s51, 0
	s_movk_i32 s1, 0x100
	v_cndmask_b32_e32 v1, v196, v197, vcc
	v_sub_u32_e32 v1, v1, v0
	s_cselect_b64 vcc, -1, 0
	v_cndmask_b32_e32 v0, v1, v0, vcc
	v_cmp_gt_i32_e32 vcc, s1, v0
	v_readlane_b32 s4, v252, 2
	v_readlane_b32 s5, v252, 3
	v_cndmask_b32_e64 v1, v205, 0, vcc
	v_cndmask_b32_e32 v2, v204, v205, vcc
	v_cmp_gt_i32_e64 s[46:47], v0, v1
	v_add_u32_e32 v1, 1, v0
	v_cmp_lt_i32_e64 s[44:45], v1, v2
	v_ashrrev_i32_e32 v1, 31, v0
	v_mad_i64_i32 v[0:1], s[30:31], s31, v204, v[0:1]
	v_mov_b64_e32 v[2:3], s[4:5]
	s_movk_i32 s1, 0x620
	v_and_b32_e32 v29, 3, v28
	s_waitcnt vmcnt(10)
	v_mad_u64_u32 v[32:33], s[30:31], v0, s1, v[2:3]
	v_mad_i32_i24 v33, v1, s1, v33
	v_cmp_lt_u32_e64 s[100:101], 1, v29
	v_lshlrev_b32_e32 v30, 4, v29
	s_mov_b64 vcc, exec
	s_and_saveexec_b64 s[30:31], vcc
	s_xor_b64 s[34:35], exec, s[30:31]
	v_mov_b32_e32 v224, 0xffffff00
	v_mov_b32_e32 v226, 0xfffffe00
	v_mov_b32_e32 v228, 0x3e3504f3
	v_mov_b32_e32 v230, 0x1400
	v_cndmask_b32_e64 v224, v224, 0, s[100:101]
	v_cndmask_b32_e64 v225, -1, 0, s[100:101]
	v_cndmask_b32_e64 v226, v226, 0, s[100:101]
	v_cndmask_b32_e64 v228, v228, 1.0, s[100:101]
	v_cndmask_b32_e64 v230, 0, v230, s[100:101]
	v_mov_b32_e32 v227, v225
	v_mov_b32_e32 v229, v228
	s_cbranch_execz .LBB0_494
	s_waitcnt vmcnt(9)
	v_and_b32_e32 v41, 16, v30
	v_lshl_add_u32 v104, s50, 5, v41
	v_lshl_add_u64 v[34:35], v[104:105], 1, v[32:33]
	v_lshl_add_u64 v[34:35], v[34:35], 0, v[224:225]
	global_load_dwordx4 v[4:7], v[34:35], off offset:256
	s_waitcnt vmcnt(0)
	v_mov_b64_e32 v[0:1], v[4:5]
	v_mov_b64_e32 v[2:3], v[6:7]
	s_and_saveexec_b64 s[30:31], s[46:47]
	s_cbranch_execz .LBB0_487
	global_load_dwordx4 v[0:3], v[34:35], off offset:-1312

; __device__ __forceinline__ float bf2f(bf16_t h) { return __uint_as_float(((unsigned)h) << 16); }
; __device__ __forceinline__ float siluf_(float x) { return x / (1.f + __expf(-x)); }
; __device__ __forceinline__ uint4 conv8_bf(const bf16_t* zr, int c, bool hp, bool hn, const float* cw, const float* cb, float scale) {
;     const bf16x8 cur = *(const bf16x8*)(zr + c);
;     bf16x8 pv = cur, nx = cur;
;     if (hp) pv = *(const bf16x8*)(zr + c - 784);
;     if (hn) nx = *(const bf16x8*)(zr + c + 784);
;     float o[8];
;     const f32x4 w0a = *(const f32x4*)(cw + c), w0b = *(const f32x4*)(cw + c + 4), w1a = *(const f32x4*)(cw + 256 + c), w1b = *(const f32x4*)(cw + 256 + c + 4);
;     const f32x4 w2a = *(const f32x4*)(cw + 512 + c), w2b = *(const f32x4*)(cw + 512 + c + 4), bba = *(const f32x4*)(cb + c), bbb = *(const f32x4*)(cb + c + 4);
; #pragma unroll
;     for (int j = 0; j < 8; ++j) {
;         const float w0 = j < 4 ? w0a[j & 3] : w0b[j & 3], w1 = j < 4 ? w1a[j & 3] : w1b[j & 3], w2 = j < 4 ? w2a[j & 3] : w2b[j & 3], bb = j < 4 ? bba[j & 3] : bbb[j & 3];
;         float a = bf2f((bf16_t)cur[j]) * w1 + bb;
;         if (hp) a += bf2f((bf16_t)pv[j]) * w0;
;         if (hn) a += bf2f((bf16_t)nx[j]) * w2;
;         o[j] = siluf_(a) * scale;
;     }
.LBB0_489:
	s_or_b64 exec, exec, s[30:31]
	v_readlane_b32 s4, v254, 44
	v_lshlrev_b64 v[24:25], 2, v[104:105]
	v_lshl_add_u64 v[24:25], v[24:25], 0, v[226:227]
	v_readlane_b32 s5, v254, 45
	v_and_b32_e32 v63, 0xffff0000, v4
	v_lshlrev_b32_e32 v62, 16, v4
	v_lshl_add_u64 v[36:37], s[4:5], 0, v[24:25]
	v_readlane_b32 s4, v254, 46
	v_readlane_b32 s5, v254, 47
	global_load_dwordx4 v[16:19], v[36:37], off offset:528
	global_load_dwordx4 v[42:45], v[36:37], off offset:512
	global_load_dwordx4 v[20:23], v[36:37], off offset:1552
	global_load_dwordx4 v[46:49], v[36:37], off offset:1536
	global_load_dwordx4 v[12:15], v[36:37], off offset:2576
	global_load_dwordx4 v[50:53], v[36:37], off offset:2560
	v_lshl_add_u64 v[38:39], s[4:5], 0, v[24:25]
	global_load_dwordx4 v[24:27], v[38:39], off offset:528
	global_load_dwordx4 v[54:57], v[38:39], off offset:512
	s_waitcnt vmcnt(8)
	v_and_b32_e32 v61, 0xffff0000, v0
	v_lshlrev_b32_e32 v60, 16, v0
	v_and_b32_e32 v59, 0xffff0000, v8
	v_lshlrev_b32_e32 v58, 16, v8
	s_movk_i32 s1, 0x50
	s_waitcnt vmcnt(0)
; __device__ __forceinline__ float bf2f(bf16_t h) { return __uint_as_float(((unsigned)h) << 16); }
; __device__ __forceinline__ unsigned pack2bf(float a, float b) { const f32x2 v = {a, b}; return __builtin_bit_cast(unsigned, __builtin_convertvector(v, bf2_t)); }
; __device__ __forceinline__ float siluf_(float x) { return x / (1.f + __expf(-x)); }
; __device__ __forceinline__ uint4 conv8_bf(const bf16_t* zr, int c, bool hp, bool hn, const float* cw, const float* cb, float scale) {
;     ...
;     for (int j = 0; j < 8; ++j) {
;         const float w0 = j < 4 ? w0a[j & 3] : w0b[j & 3], w1 = j < 4 ? w1a[j & 3] : w1b[j & 3], w2 = j < 4 ? w2a[j & 3] : w2b[j & 3], bb = j < 4 ? bba[j & 3] : bbb[j & 3];
;         float a = bf2f((bf16_t)cur[j]) * w1 + bb;
;         if (hp) a += bf2f((bf16_t)pv[j]) * w0;
;         if (hn) a += bf2f((bf16_t)nx[j]) * w2;
;         o[j] = siluf_(a) * scale;
;     }
;     uint4 w; w.x = pack2bf(o[0], o[1]); w.y = pack2bf(o[2], o[3]); w.z = pack2bf(o[4], o[5]); w.w = pack2bf(o[6], o[7]);
; __device__ __forceinline__ void mlstm_out_unit(const Params& p, int layer, int uci, char* smem) {
;     ...
;         if (part < 2) { const int kc = part * 16;
;             *(uint4*)(smem + MO_Q + s * 80 + kc * 2) = conv8_bf(zr, h * 32 + kc, hp, hn, cw, cb, 0.17677669529663687f);
;             *(uint4*)(smem + MO_Q + s * 80 + kc * 2 + 16) = conv8_bf(zr, h * 32 + kc + 8, hp, hn, cw, cb, 0.17677669529663687f); }
;         else { const int kc = (part - 2) * 16;
;             *(uint4*)(smem + MO_K + s * 80 + kc * 2) = conv8_bf(zr, 128 + h * 32 + kc, hp, hn, cw, cb, 1.f);
;             *(uint4*)(smem + MO_K + s * 80 + kc * 2 + 16) = conv8_bf(zr, 128 + h * 32 + kc + 8, hp, hn, cw, cb, 1.f); }
	v_pk_fma_f32 v[46:47], v[46:47], v[62:63], v[54:55]
	s_nop 0
	v_pk_fma_f32 v[42:43], v[42:43], v[60:61], v[46:47]
	s_nop 0
	v_cndmask_b32_e64 v43, v47, v43, s[46:47]
	v_cndmask_b32_e64 v42, v46, v42, s[46:47]
	v_pk_fma_f32 v[46:47], v[50:51], v[58:59], v[42:43]
	s_nop 0
	v_cndmask_b32_e64 v4, v42, v46, s[44:45]
	v_cndmask_b32_e64 v0, v43, v47, s[44:45]
	v_mul_f32_e32 v8, 0xbfb8aa3b, v4
	v_exp_f32_e32 v42, v8
	v_mul_f32_e32 v8, 0xbfb8aa3b, v0
	v_exp_f32_e32 v43, v8
	s_nop 0
	v_pk_add_f32 v[42:43], v[42:43], 1.0 op_sel_hi:[1,0]
	s_nop 0
	v_div_scale_f32 v8, s[30:31], v43, v43, v0
	v_rcp_f32_e32 v46, v8
	s_nop 0
	v_fma_f32 v47, -v8, v46, 1.0
	v_fmac_f32_e32 v46, v47, v46
	v_div_scale_f32 v47, vcc, v0, v43, v0
	v_mul_f32_e32 v50, v47, v46
	v_fma_f32 v51, -v8, v50, v47
	v_fmac_f32_e32 v50, v51, v46
	v_fma_f32 v8, -v8, v50, v47
	v_div_fmas_f32 v8, v8, v46, v50
	v_div_fixup_f32 v0, v8, v43, v0
	v_div_scale_f32 v8, s[30:31], v42, v42, v4
	v_rcp_f32_e32 v43, v8
	s_nop 0
	v_fma_f32 v46, -v8, v43, 1.0
	v_fmac_f32_e32 v43, v46, v43
	v_div_scale_f32 v46, vcc, v4, v42, v4
	v_mul_f32_e32 v47, v46, v43
	v_fma_f32 v50, -v8, v47, v46
	v_fmac_f32_e32 v47, v50, v43
	v_fma_f32 v8, -v8, v47, v46
	v_div_fmas_f32 v8, v8, v43, v47
	v_and_b32_e32 v47, 0xffff0000, v5
	v_lshlrev_b32_e32 v46, 16, v5
	v_div_fixup_f32 v4, v8, v42, v4
	v_and_b32_e32 v43, 0xffff0000, v9
	v_lshlrev_b32_e32 v42, 16, v9
	v_and_b32_e32 v9, 0xffff0000, v1
	v_lshlrev_b32_e32 v8, 16, v1
	v_pk_fma_f32 v[46:47], v[48:49], v[46:47], v[56:57]
	v_mul_f32_e32 v231, v228, v4
	v_mul_f32_e32 v232, v228, v0
	v_cvt_pk_bf16_f32 v0, v231, v232
	v_pk_fma_f32 v[8:9], v[44:45], v[8:9], v[46:47]
	v_mul_lo_u32 v4, v31, s1
	v_cndmask_b32_e64 v9, v47, v9, s[46:47]
	v_cndmask_b32_e64 v8, v46, v8, s[46:47]
	v_pk_fma_f32 v[42:43], v[52:53], v[42:43], v[8:9]
	s_nop 0
	v_cndmask_b32_e64 v1, v9, v43, s[44:45]
	v_cndmask_b32_e64 v5, v8, v42, s[44:45]
	v_mul_f32_e32 v8, 0xbfb8aa3b, v5
	v_mul_f32_e32 v9, 0xbfb8aa3b, v1
	v_exp_f32_e32 v8, v8
	v_exp_f32_e32 v9, v9
	s_nop 0
	v_pk_add_f32 v[8:9], v[8:9], 1.0 op_sel_hi:[1,0]
	s_nop 0
	v_div_scale_f32 v42, s[30:31], v9, v9, v1
	v_rcp_f32_e32 v43, v42
	s_nop 0
	v_fma_f32 v44, -v42, v43, 1.0
	v_fmac_f32_e32 v43, v44, v43
	v_div_scale_f32 v44, vcc, v1, v9, v1
	v_mul_f32_e32 v45, v44, v43
	v_fma_f32 v46, -v42, v45, v44
	v_fmac_f32_e32 v45, v46, v43
	v_fma_f32 v42, -v42, v45, v44
	v_div_fmas_f32 v42, v42, v43, v45
	v_div_fixup_f32 v1, v42, v9, v1
	v_div_scale_f32 v9, s[30:31], v8, v8, v5
	v_rcp_f32_e32 v42, v9
	s_nop 0
	v_fma_f32 v43, -v9, v42, 1.0
	v_fmac_f32_e32 v42, v43, v42
	v_div_scale_f32 v43, vcc, v5, v8, v5
	v_mul_f32_e32 v44, v43, v42
	v_fma_f32 v45, -v9, v44, v43
	v_fmac_f32_e32 v44, v45, v42
	v_fma_f32 v9, -v9, v44, v43
	v_div_fmas_f32 v9, v9, v42, v44
	v_and_b32_e32 v45, 0xffff0000, v6
	v_lshlrev_b32_e32 v44, 16, v6
	v_and_b32_e32 v43, 0xffff0000, v2
	v_lshlrev_b32_e32 v42, 16, v2
	v_pk_fma_f32 v[20:21], v[20:21], v[44:45], v[24:25]
	v_div_fixup_f32 v5, v9, v8, v5
	v_pk_fma_f32 v[16:17], v[16:17], v[42:43], v[20:21]
	v_and_b32_e32 v9, 0xffff0000, v10
	v_lshlrev_b32_e32 v8, 16, v10
	v_cndmask_b32_e64 v17, v21, v17, s[46:47]
	v_cndmask_b32_e64 v16, v20, v16, s[46:47]
	v_pk_fma_f32 v[8:9], v[12:13], v[8:9], v[16:17]
	v_mul_f32_e32 v231, v228, v5
	v_mul_f32_e32 v232, v228, v1
	v_cvt_pk_bf16_f32 v1, v231, v232
	v_cndmask_b32_e64 v2, v17, v9, s[44:45]
	v_cndmask_b32_e64 v6, v16, v8, s[44:45]
	v_mul_f32_e32 v8, 0xbfb8aa3b, v6
	v_mul_f32_e32 v9, 0xbfb8aa3b, v2
	v_exp_f32_e32 v8, v8
	v_exp_f32_e32 v9, v9
	s_nop 0
	v_pk_add_f32 v[8:9], v[8:9], 1.0 op_sel_hi:[1,0]
	s_nop 0
	v_div_scale_f32 v10, s[30:31], v9, v9, v2
	v_rcp_f32_e32 v12, v10
	s_nop 0
	v_fma_f32 v13, -v10, v12, 1.0
	v_fmac_f32_e32 v12, v13, v12
	v_div_scale_f32 v13, vcc, v2, v9, v2
	v_mul_f32_e32 v16, v13, v12
	v_fma_f32 v17, -v10, v16, v13
	v_fmac_f32_e32 v16, v17, v12
	v_fma_f32 v10, -v10, v16, v13
	v_div_fmas_f32 v10, v10, v12, v16
	v_div_fixup_f32 v10, v10, v9, v2
	v_div_scale_f32 v2, s[30:31], v8, v8, v6
	v_rcp_f32_e32 v9, v2
	s_nop 0
	v_fma_f32 v12, -v2, v9, 1.0
	v_fmac_f32_e32 v9, v12, v9
	v_div_scale_f32 v12, vcc, v6, v8, v6
	v_mul_f32_e32 v13, v12, v9
	v_fma_f32 v16, -v2, v13, v12
	v_fmac_f32_e32 v13, v16, v9
	v_fma_f32 v2, -v2, v13, v12
	v_div_fmas_f32 v2, v2, v9, v13
	v_div_fixup_f32 v12, v2, v8, v6
	v_and_b32_e32 v9, 0xffff0000, v7
	v_lshlrev_b32_e32 v8, 16, v7
	v_pk_fma_f32 v[6:7], v[22:23], v[8:9], v[26:27]
	v_and_b32_e32 v9, 0xffff0000, v3
	v_lshlrev_b32_e32 v8, 16, v3
	v_pk_fma_f32 v[2:3], v[18:19], v[8:9], v[6:7]
	s_nop 0
	v_cndmask_b32_e64 v3, v7, v3, s[46:47]
	v_cndmask_b32_e64 v2, v6, v2, s[46:47]
	v_and_b32_e32 v7, 0xffff0000, v11
	v_lshlrev_b32_e32 v6, 16, v11
	v_pk_fma_f32 v[6:7], v[14:15], v[6:7], v[2:3]
	s_nop 0
	v_cndmask_b32_e64 v7, v3, v7, s[44:45]
	v_cndmask_b32_e64 v6, v2, v6, s[44:45]
	v_mul_f32_e32 v2, 0xbfb8aa3b, v6
	v_mul_f32_e32 v3, 0xbfb8aa3b, v7
	v_exp_f32_e32 v2, v2
	v_exp_f32_e32 v3, v3
	s_nop 0
	v_pk_add_f32 v[2:3], v[2:3], 1.0 op_sel_hi:[1,0]
	s_nop 0
	v_div_scale_f32 v8, s[30:31], v3, v3, v7
	v_rcp_f32_e32 v9, v8
	s_nop 0
	v_fma_f32 v11, -v8, v9, 1.0
	v_fmac_f32_e32 v9, v11, v9
	v_div_scale_f32 v11, vcc, v7, v3, v7
	v_mul_f32_e32 v13, v11, v9
	v_fma_f32 v14, -v8, v13, v11
	v_fmac_f32_e32 v13, v14, v9
	v_fma_f32 v8, -v8, v13, v11
	v_div_fmas_f32 v8, v8, v9, v13
	v_div_fixup_f32 v3, v8, v3, v7
	v_div_scale_f32 v7, s[30:31], v2, v2, v6
	v_rcp_f32_e32 v8, v7
	s_nop 0
	v_fma_f32 v9, -v7, v8, 1.0
	v_fmac_f32_e32 v8, v9, v8
	v_div_scale_f32 v9, vcc, v6, v2, v6
	v_mul_f32_e32 v11, v9, v8
	v_fma_f32 v13, -v7, v11, v9
	v_fmac_f32_e32 v11, v13, v8
	v_fma_f32 v7, -v7, v11, v9
	v_div_fmas_f32 v7, v7, v8, v11
	v_div_fixup_f32 v6, v7, v2, v6
	v_mul_f32_e32 v231, v228, v12
	v_mul_f32_e32 v232, v228, v10
	v_cvt_pk_bf16_f32 v2, v231, v232
	v_mul_f32_e32 v231, v228, v6
	v_mul_f32_e32 v232, v228, v3
	v_cvt_pk_bf16_f32 v3, v231, v232
	v_lshl_add_u32 v12, v41, 1, v4
	v_add_u32_e32 v233, v230, v12
	ds_write_b128 v233, v[0:3]
	global_load_dwordx4 v[0:3], v[34:35], off offset:272
	s_waitcnt vmcnt(0)
	v_mov_b64_e32 v[6:7], v[2:3]
	v_mov_b64_e32 v[4:5], v[0:1]
	s_and_saveexec_b64 s[30:31], s[46:47]
	s_cbranch_execz .LBB0_491
	global_load_dwordx4 v[4:7], v[34:35], off offset:-1296

; __device__ __forceinline__ float bf2f(bf16_t h) { return __uint_as_float(((unsigned)h) << 16); }
; __device__ __forceinline__ unsigned pack2bf(float a, float b) { const f32x2 v = {a, b}; return __builtin_bit_cast(unsigned, __builtin_convertvector(v, bf2_t)); }
; __device__ __forceinline__ float siluf_(float x) { return x / (1.f + __expf(-x)); }
; __device__ __forceinline__ uint4 conv8_bf(const bf16_t* zr, int c, bool hp, bool hn, const float* cw, const float* cb, float scale) {
;     ...
;     for (int j = 0; j < 8; ++j) {
;         const float w0 = j < 4 ? w0a[j & 3] : w0b[j & 3], w1 = j < 4 ? w1a[j & 3] : w1b[j & 3], w2 = j < 4 ? w2a[j & 3] : w2b[j & 3], bb = j < 4 ? bba[j & 3] : bbb[j & 3];
;         float a = bf2f((bf16_t)cur[j]) * w1 + bb;
;         if (hp) a += bf2f((bf16_t)pv[j]) * w0;
;         if (hn) a += bf2f((bf16_t)nx[j]) * w2;
;         o[j] = siluf_(a) * scale;
;     }
;     uint4 w; w.x = pack2bf(o[0], o[1]); w.y = pack2bf(o[2], o[3]); w.z = pack2bf(o[4], o[5]); w.w = pack2bf(o[6], o[7]);
; __device__ __forceinline__ void mlstm_out_unit(const Params& p, int layer, int uci, char* smem) {
;     ...
;         if (part < 2) { const int kc = part * 16;
;             *(uint4*)(smem + MO_Q + s * 80 + kc * 2) = conv8_bf(zr, h * 32 + kc, hp, hn, cw, cb, 0.17677669529663687f);
;             *(uint4*)(smem + MO_Q + s * 80 + kc * 2 + 16) = conv8_bf(zr, h * 32 + kc + 8, hp, hn, cw, cb, 0.17677669529663687f); }
;         else { const int kc = (part - 2) * 16;
;             *(uint4*)(smem + MO_K + s * 80 + kc * 2) = conv8_bf(zr, 128 + h * 32 + kc, hp, hn, cw, cb, 1.f);
;             *(uint4*)(smem + MO_K + s * 80 + kc * 2 + 16) = conv8_bf(zr, 128 + h * 32 + kc + 8, hp, hn, cw, cb, 1.f); }
.LBB0_493:
	s_or_b64 exec, exec, s[30:31]
	v_add_u32_e32 v41, v230, v12
	global_load_dwordx4 v[16:19], v[36:37], off offset:560
	global_load_dwordx4 v[42:45], v[36:37], off offset:544
	global_load_dwordx4 v[20:23], v[36:37], off offset:1584
	global_load_dwordx4 v[46:49], v[36:37], off offset:1568
	global_load_dwordx4 v[12:15], v[36:37], off offset:2608
	s_nop 0
	global_load_dwordx4 v[34:37], v[36:37], off offset:2592
	s_nop 0
	global_load_dwordx4 v[24:27], v[38:39], off offset:560
	global_load_dwordx4 v[50:53], v[38:39], off offset:544
	v_and_b32_e32 v57, 0xffff0000, v0
	v_lshlrev_b32_e32 v56, 16, v0
	s_waitcnt vmcnt(8)
	v_and_b32_e32 v55, 0xffff0000, v4
	v_lshlrev_b32_e32 v54, 16, v4
	v_and_b32_e32 v39, 0xffff0000, v8
	v_lshlrev_b32_e32 v38, 16, v8
	s_waitcnt vmcnt(0)
	v_pk_fma_f32 v[46:47], v[46:47], v[56:57], v[50:51]
	s_nop 0
	v_pk_fma_f32 v[42:43], v[42:43], v[54:55], v[46:47]
	s_nop 0
	v_cndmask_b32_e64 v43, v47, v43, s[46:47]
	v_cndmask_b32_e64 v42, v46, v42, s[46:47]
	v_pk_fma_f32 v[34:35], v[34:35], v[38:39], v[42:43]
	s_nop 0
	v_cndmask_b32_e64 v4, v42, v34, s[44:45]
	v_cndmask_b32_e64 v0, v43, v35, s[44:45]
	v_mul_f32_e32 v8, 0xbfb8aa3b, v4
	v_exp_f32_e32 v34, v8
	v_mul_f32_e32 v8, 0xbfb8aa3b, v0
	v_exp_f32_e32 v35, v8
	s_nop 0
	v_pk_add_f32 v[34:35], v[34:35], 1.0 op_sel_hi:[1,0]
	s_nop 0
	v_div_scale_f32 v8, s[30:31], v35, v35, v0
	v_rcp_f32_e32 v38, v8
	s_nop 0
	v_fma_f32 v39, -v8, v38, 1.0
	v_fmac_f32_e32 v38, v39, v38
	v_div_scale_f32 v39, vcc, v0, v35, v0
	v_mul_f32_e32 v42, v39, v38
	v_fma_f32 v43, -v8, v42, v39
	v_fmac_f32_e32 v42, v43, v38
	v_fma_f32 v8, -v8, v42, v39
	v_div_fmas_f32 v8, v8, v38, v42
	v_div_fixup_f32 v35, v8, v35, v0
	v_div_scale_f32 v0, s[30:31], v34, v34, v4
	v_rcp_f32_e32 v8, v0
	s_nop 0
	v_fma_f32 v38, -v0, v8, 1.0
	v_fmac_f32_e32 v8, v38, v8
	v_div_scale_f32 v38, vcc, v4, v34, v4
	v_mul_f32_e32 v39, v38, v8
	v_fma_f32 v42, -v0, v39, v38
	v_fmac_f32_e32 v39, v42, v8
	v_fma_f32 v0, -v0, v39, v38
	v_div_fmas_f32 v0, v0, v8, v39
	v_div_fixup_f32 v34, v0, v34, v4
	v_and_b32_e32 v39, 0xffff0000, v9
	v_lshlrev_b32_e32 v38, 16, v9
	v_and_b32_e32 v9, 0xffff0000, v5
	v_lshlrev_b32_e32 v8, 16, v5
	v_and_b32_e32 v5, 0xffff0000, v1
	v_lshlrev_b32_e32 v4, 16, v1
	v_pk_fma_f32 v[0:1], v[48:49], v[4:5], v[52:53]
	s_nop 0
	v_pk_fma_f32 v[4:5], v[44:45], v[8:9], v[0:1]
	s_nop 0
	v_cndmask_b32_e64 v1, v1, v5, s[46:47]
	v_cndmask_b32_e64 v0, v0, v4, s[46:47]
	v_pk_fma_f32 v[4:5], v[36:37], v[38:39], v[0:1]
	s_nop 0
	v_cndmask_b32_e64 v5, v1, v5, s[44:45]
	v_cndmask_b32_e64 v4, v0, v4, s[44:45]
	v_mul_f32_e32 v0, 0xbfb8aa3b, v4
	v_mul_f32_e32 v1, 0xbfb8aa3b, v5
	v_exp_f32_e32 v0, v0
	v_exp_f32_e32 v1, v1
	s_nop 0
	v_pk_add_f32 v[0:1], v[0:1], 1.0 op_sel_hi:[1,0]
	s_nop 0
	v_div_scale_f32 v8, s[30:31], v1, v1, v5
	v_rcp_f32_e32 v9, v8
	s_nop 0
	v_fma_f32 v36, -v8, v9, 1.0
	v_fmac_f32_e32 v9, v36, v9
	v_div_scale_f32 v36, vcc, v5, v1, v5
	v_mul_f32_e32 v37, v36, v9
	v_fma_f32 v38, -v8, v37, v36
	v_fmac_f32_e32 v37, v38, v9
	v_fma_f32 v8, -v8, v37, v36
	v_div_fmas_f32 v8, v8, v9, v37
	v_div_fixup_f32 v1, v8, v1, v5
	v_div_scale_f32 v5, s[30:31], v0, v0, v4
	v_rcp_f32_e32 v8, v5
	s_nop 0
	v_fma_f32 v9, -v5, v8, 1.0
	v_fmac_f32_e32 v8, v9, v8
	v_div_scale_f32 v9, vcc, v4, v0, v4
	v_mul_f32_e32 v36, v9, v8
	v_fma_f32 v37, -v5, v36, v9
	v_fmac_f32_e32 v36, v37, v8
	v_fma_f32 v5, -v5, v36, v9
	v_div_fmas_f32 v5, v5, v8, v36
	v_and_b32_e32 v37, 0xffff0000, v2
	v_lshlrev_b32_e32 v36, 16, v2
	v_and_b32_e32 v9, 0xffff0000, v6
	v_lshlrev_b32_e32 v8, 16, v6
	v_pk_fma_f32 v[20:21], v[20:21], v[36:37], v[24:25]
	v_div_fixup_f32 v0, v5, v0, v4
	v_pk_fma_f32 v[8:9], v[16:17], v[8:9], v[20:21]
	v_and_b32_e32 v5, 0xffff0000, v10
	v_lshlrev_b32_e32 v4, 16, v10
	v_cndmask_b32_e64 v9, v21, v9, s[46:47]
	v_cndmask_b32_e64 v8, v20, v8, s[46:47]
	v_pk_fma_f32 v[4:5], v[12:13], v[4:5], v[8:9]
	s_nop 0
	v_cndmask_b32_e64 v2, v9, v5, s[44:45]
	v_cndmask_b32_e64 v6, v8, v4, s[44:45]
	v_mul_f32_e32 v4, 0xbfb8aa3b, v6
	v_mul_f32_e32 v5, 0xbfb8aa3b, v2
	v_exp_f32_e32 v4, v4
	v_exp_f32_e32 v5, v5
	s_nop 0
	v_pk_add_f32 v[4:5], v[4:5], 1.0 op_sel_hi:[1,0]
	s_nop 0
	v_div_scale_f32 v8, s[30:31], v5, v5, v2
	v_rcp_f32_e32 v9, v8
	s_nop 0
	v_fma_f32 v10, -v8, v9, 1.0
	v_fmac_f32_e32 v9, v10, v9
	v_div_scale_f32 v10, vcc, v2, v5, v2
	v_mul_f32_e32 v12, v10, v9
	v_fma_f32 v13, -v8, v12, v10
	v_fmac_f32_e32 v12, v13, v9
	v_fma_f32 v8, -v8, v12, v10
	v_div_fmas_f32 v8, v8, v9, v12
	v_div_fixup_f32 v5, v8, v5, v2
	v_div_scale_f32 v2, s[30:31], v4, v4, v6
	v_rcp_f32_e32 v8, v2
	s_nop 0
	v_fma_f32 v9, -v2, v8, 1.0
	v_fmac_f32_e32 v8, v9, v8
	v_div_scale_f32 v9, vcc, v6, v4, v6
	v_mul_f32_e32 v10, v9, v8
	v_fma_f32 v12, -v2, v10, v9
	v_fmac_f32_e32 v10, v12, v8
	v_fma_f32 v2, -v2, v10, v9
	v_div_fmas_f32 v2, v2, v8, v10
	v_and_b32_e32 v9, 0xffff0000, v3
	v_lshlrev_b32_e32 v8, 16, v3
	v_div_fixup_f32 v4, v2, v4, v6
	v_pk_fma_f32 v[2:3], v[22:23], v[8:9], v[26:27]
	v_and_b32_e32 v9, 0xffff0000, v7
	v_lshlrev_b32_e32 v8, 16, v7
	v_pk_fma_f32 v[6:7], v[18:19], v[8:9], v[2:3]
	s_nop 0
	v_cndmask_b32_e64 v3, v3, v7, s[46:47]
	v_cndmask_b32_e64 v2, v2, v6, s[46:47]
	v_and_b32_e32 v7, 0xffff0000, v11
	v_lshlrev_b32_e32 v6, 16, v11
	v_pk_fma_f32 v[6:7], v[14:15], v[6:7], v[2:3]
	s_nop 0
	v_cndmask_b32_e64 v7, v3, v7, s[44:45]
	v_cndmask_b32_e64 v6, v2, v6, s[44:45]
	v_mul_f32_e32 v2, 0xbfb8aa3b, v6
	v_mul_f32_e32 v3, 0xbfb8aa3b, v7
	v_exp_f32_e32 v2, v2
	v_exp_f32_e32 v3, v3
	s_nop 0
	v_pk_add_f32 v[2:3], v[2:3], 1.0 op_sel_hi:[1,0]
	s_nop 0
	v_div_scale_f32 v8, s[30:31], v3, v3, v7
	v_rcp_f32_e32 v9, v8
	s_nop 0
	v_fma_f32 v10, -v8, v9, 1.0
	v_fmac_f32_e32 v9, v10, v9
	v_div_scale_f32 v10, vcc, v7, v3, v7
	v_mul_f32_e32 v11, v10, v9
	v_fma_f32 v12, -v8, v11, v10
	v_fmac_f32_e32 v11, v12, v9
	v_fma_f32 v8, -v8, v11, v10
	v_div_fmas_f32 v8, v8, v9, v11
	v_div_fixup_f32 v3, v8, v3, v7
	v_div_scale_f32 v7, s[30:31], v2, v2, v6
	v_rcp_f32_e32 v8, v7
	s_nop 0
	v_fma_f32 v9, -v7, v8, 1.0
	v_fmac_f32_e32 v8, v9, v8
	v_div_scale_f32 v9, vcc, v6, v2, v6
	v_mul_f32_e32 v10, v9, v8
	v_fma_f32 v11, -v7, v10, v9
	v_fmac_f32_e32 v10, v11, v8
	v_fma_f32 v7, -v7, v10, v9
	v_div_fmas_f32 v7, v7, v8, v10
	v_div_fixup_f32 v2, v7, v2, v6
	v_pk_mul_f32 v[0:1], v[0:1], v[228:229]
	v_pk_mul_f32 v[34:35], v[34:35], v[228:229]
	v_pk_mul_f32 v[4:5], v[4:5], v[228:229]
	v_pk_mul_f32 v[2:3], v[2:3], v[228:229]
